# select scoring loop: redundant per-tile key<N exec mask removed, float->key transform via ashr/or/xor
# baseline (speedup 1.0000x reference)
.Lsel_blk0:
	s_waitcnt vmcnt(6)
	v_mfma_f32_32x32x16_bf16 v[0:15], v[18:21], v[136:139], 0
	v_mfma_f32_32x32x16_bf16 v[0:15], v[22:25], v[140:143], v[0:15]
	v_min_u32_e32 v168, s7, v170
	v_lshlrev_b32_e32 v168, 6, v168
	v_lshl_add_u64 v[134:135], v[44:45], 0, v[168:169]
	global_load_dwordx4 v[136:139], v[134:135], off
	global_load_dwordx4 v[140:143], v[134:135], off offset:32
	v_add_u32_e32 v170, 0x80, v170
	s_nop 5
	v_max_f32_e32 v0, 0, v0
	v_max_f32_e32 v8, 0, v8
	v_max_f32_e32 v1, 0, v1
	v_max_f32_e32 v9, 0, v9
	v_max_f32_e32 v2, 0, v2
	v_max_f32_e32 v10, 0, v10
	v_max_f32_e32 v3, 0, v3
	v_max_f32_e32 v11, 0, v11
	v_max_f32_e32 v4, 0, v4
	v_max_f32_e32 v12, 0, v12
	v_max_f32_e32 v5, 0, v5
	v_max_f32_e32 v13, 0, v13
	v_max_f32_e32 v6, 0, v6
	v_max_f32_e32 v14, 0, v14
	v_max_f32_e32 v7, 0, v7
	v_max_f32_e32 v15, 0, v15
	v_mul_f32_e32 v53, v38, v0
	v_mul_f32_e32 v52, v30, v8
	v_fmac_f32_e32 v53, v39, v1
	v_fmac_f32_e32 v52, v31, v9
	v_fmac_f32_e32 v53, v40, v2
	v_fmac_f32_e32 v52, v32, v10
	v_fmac_f32_e32 v53, v41, v3
	v_fmac_f32_e32 v52, v33, v11
	v_fmac_f32_e32 v53, v34, v4
	v_fmac_f32_e32 v52, v26, v12
	v_fmac_f32_e32 v53, v35, v5
	v_fmac_f32_e32 v52, v27, v13
	v_fmac_f32_e32 v53, v36, v6
	v_fmac_f32_e32 v52, v28, v14
	v_fma_f32 v1, v37, v7, v53
	v_fma_f32 v0, v29, v15, v52
	v_ashrrev_i32_e32 v2, 31, v1
	v_ashrrev_i32_e32 v3, 31, v0
	v_or_b32_e32 v2, 0x80000000, v2
	v_or_b32_e32 v3, 0x80000000, v3
	v_xor_b32_e32 v1, v1, v2
	v_xor_b32_e32 v0, v0, v3
	ds_write2st64_b32 v48, v1, v0 offset1:65
	v_add_u32_e32 v48, 0x200, v48
	v_add_u32_e32 v49, 0x80, v49
	s_add_u32 s2, s2, 1
	s_cmp_lt_u32 s2, s3
	s_cbranch_scc0 .LBB0_890
.Lsel_blk1:
	s_waitcnt vmcnt(6)
	v_mfma_f32_32x32x16_bf16 v[0:15], v[18:21], v[144:147], 0
	v_mfma_f32_32x32x16_bf16 v[0:15], v[22:25], v[148:151], v[0:15]
	v_min_u32_e32 v168, s7, v170
	v_lshlrev_b32_e32 v168, 6, v168
	v_lshl_add_u64 v[134:135], v[44:45], 0, v[168:169]
	global_load_dwordx4 v[144:147], v[134:135], off
	global_load_dwordx4 v[148:151], v[134:135], off offset:32
	v_add_u32_e32 v170, 0x80, v170
	s_nop 5
	v_max_f32_e32 v0, 0, v0
	v_max_f32_e32 v8, 0, v8
	v_max_f32_e32 v1, 0, v1
	v_max_f32_e32 v9, 0, v9
	v_max_f32_e32 v2, 0, v2
	v_max_f32_e32 v10, 0, v10
	v_max_f32_e32 v3, 0, v3
	v_max_f32_e32 v11, 0, v11
	v_max_f32_e32 v4, 0, v4
	v_max_f32_e32 v12, 0, v12
	v_max_f32_e32 v5, 0, v5
	v_max_f32_e32 v13, 0, v13
	v_max_f32_e32 v6, 0, v6
	v_max_f32_e32 v14, 0, v14
	v_max_f32_e32 v7, 0, v7
	v_max_f32_e32 v15, 0, v15
	v_mul_f32_e32 v53, v38, v0
	v_mul_f32_e32 v52, v30, v8
	v_fmac_f32_e32 v53, v39, v1
	v_fmac_f32_e32 v52, v31, v9
	v_fmac_f32_e32 v53, v40, v2
	v_fmac_f32_e32 v52, v32, v10
	v_fmac_f32_e32 v53, v41, v3
	v_fmac_f32_e32 v52, v33, v11
	v_fmac_f32_e32 v53, v34, v4
	v_fmac_f32_e32 v52, v26, v12
	v_fmac_f32_e32 v53, v35, v5
	v_fmac_f32_e32 v52, v27, v13
	v_fmac_f32_e32 v53, v36, v6
	v_fmac_f32_e32 v52, v28, v14
	v_fma_f32 v1, v37, v7, v53
	v_fma_f32 v0, v29, v15, v52
	v_ashrrev_i32_e32 v2, 31, v1
	v_ashrrev_i32_e32 v3, 31, v0
	v_or_b32_e32 v2, 0x80000000, v2
	v_or_b32_e32 v3, 0x80000000, v3
	v_xor_b32_e32 v1, v1, v2
	v_xor_b32_e32 v0, v0, v3
	ds_write2st64_b32 v48, v1, v0 offset1:65
	v_add_u32_e32 v48, 0x200, v48
	v_add_u32_e32 v49, 0x80, v49
	s_add_u32 s2, s2, 1
	s_cmp_lt_u32 s2, s3
	s_cbranch_scc0 .LBB0_890
.Lsel_blk2:
	s_waitcnt vmcnt(6)
	v_mfma_f32_32x32x16_bf16 v[0:15], v[18:21], v[152:155], 0
	v_mfma_f32_32x32x16_bf16 v[0:15], v[22:25], v[156:159], v[0:15]
	v_min_u32_e32 v168, s7, v170
	v_lshlrev_b32_e32 v168, 6, v168
	v_lshl_add_u64 v[134:135], v[44:45], 0, v[168:169]
	global_load_dwordx4 v[152:155], v[134:135], off
	global_load_dwordx4 v[156:159], v[134:135], off offset:32
	v_add_u32_e32 v170, 0x80, v170
	s_nop 5
	v_max_f32_e32 v0, 0, v0
	v_max_f32_e32 v8, 0, v8
	v_max_f32_e32 v1, 0, v1
	v_max_f32_e32 v9, 0, v9
	v_max_f32_e32 v2, 0, v2
	v_max_f32_e32 v10, 0, v10
	v_max_f32_e32 v3, 0, v3
	v_max_f32_e32 v11, 0, v11
	v_max_f32_e32 v4, 0, v4
	v_max_f32_e32 v12, 0, v12
	v_max_f32_e32 v5, 0, v5
	v_max_f32_e32 v13, 0, v13
	v_max_f32_e32 v6, 0, v6
	v_max_f32_e32 v14, 0, v14
	v_max_f32_e32 v7, 0, v7
	v_max_f32_e32 v15, 0, v15
	v_mul_f32_e32 v53, v38, v0
	v_mul_f32_e32 v52, v30, v8
	v_fmac_f32_e32 v53, v39, v1
	v_fmac_f32_e32 v52, v31, v9
	v_fmac_f32_e32 v53, v40, v2
	v_fmac_f32_e32 v52, v32, v10
	v_fmac_f32_e32 v53, v41, v3
	v_fmac_f32_e32 v52, v33, v11
	v_fmac_f32_e32 v53, v34, v4
	v_fmac_f32_e32 v52, v26, v12
	v_fmac_f32_e32 v53, v35, v5
	v_fmac_f32_e32 v52, v27, v13
	v_fmac_f32_e32 v53, v36, v6
	v_fmac_f32_e32 v52, v28, v14
	v_fma_f32 v1, v37, v7, v53
	v_fma_f32 v0, v29, v15, v52
	v_ashrrev_i32_e32 v2, 31, v1
	v_ashrrev_i32_e32 v3, 31, v0
	v_or_b32_e32 v2, 0x80000000, v2
	v_or_b32_e32 v3, 0x80000000, v3
	v_xor_b32_e32 v1, v1, v2
	v_xor_b32_e32 v0, v0, v3
	ds_write2st64_b32 v48, v1, v0 offset1:65
	v_add_u32_e32 v48, 0x200, v48
	v_add_u32_e32 v49, 0x80, v49
	s_add_u32 s2, s2, 1
	s_cmp_lt_u32 s2, s3
	s_cbranch_scc0 .LBB0_890
.Lsel_blk3:
	s_waitcnt vmcnt(6)
	v_mfma_f32_32x32x16_bf16 v[0:15], v[18:21], v[160:163], 0
	v_mfma_f32_32x32x16_bf16 v[0:15], v[22:25], v[164:167], v[0:15]
	v_min_u32_e32 v168, s7, v170
	v_lshlrev_b32_e32 v168, 6, v168
	v_lshl_add_u64 v[134:135], v[44:45], 0, v[168:169]
	global_load_dwordx4 v[160:163], v[134:135], off
	global_load_dwordx4 v[164:167], v[134:135], off offset:32
	v_add_u32_e32 v170, 0x80, v170
	s_nop 5
	v_max_f32_e32 v0, 0, v0
	v_max_f32_e32 v8, 0, v8
	v_max_f32_e32 v1, 0, v1
	v_max_f32_e32 v9, 0, v9
	v_max_f32_e32 v2, 0, v2
	v_max_f32_e32 v10, 0, v10
	v_max_f32_e32 v3, 0, v3
	v_max_f32_e32 v11, 0, v11
	v_max_f32_e32 v4, 0, v4
	v_max_f32_e32 v12, 0, v12
	v_max_f32_e32 v5, 0, v5
	v_max_f32_e32 v13, 0, v13
	v_max_f32_e32 v6, 0, v6
	v_max_f32_e32 v14, 0, v14
	v_max_f32_e32 v7, 0, v7
	v_max_f32_e32 v15, 0, v15
	v_mul_f32_e32 v53, v38, v0
	v_mul_f32_e32 v52, v30, v8
	v_fmac_f32_e32 v53, v39, v1
	v_fmac_f32_e32 v52, v31, v9
	v_fmac_f32_e32 v53, v40, v2
	v_fmac_f32_e32 v52, v32, v10
	v_fmac_f32_e32 v53, v41, v3
	v_fmac_f32_e32 v52, v33, v11
	v_fmac_f32_e32 v53, v34, v4
	v_fmac_f32_e32 v52, v26, v12
	v_fmac_f32_e32 v53, v35, v5
	v_fmac_f32_e32 v52, v27, v13
	v_fmac_f32_e32 v53, v36, v6
	v_fmac_f32_e32 v52, v28, v14
	v_fma_f32 v1, v37, v7, v53
	v_fma_f32 v0, v29, v15, v52
	v_ashrrev_i32_e32 v2, 31, v1
	v_ashrrev_i32_e32 v3, 31, v0
	v_or_b32_e32 v2, 0x80000000, v2
	v_or_b32_e32 v3, 0x80000000, v3
	v_xor_b32_e32 v1, v1, v2
	v_xor_b32_e32 v0, v0, v3
	ds_write2st64_b32 v48, v1, v0 offset1:65
	v_add_u32_e32 v48, 0x200, v48
	v_add_u32_e32 v49, 0x80, v49
	s_add_u32 s2, s2, 1
	s_cmp_lt_u32 s2, s3
	s_cbranch_scc1 .Lsel_blk0
